# out-proj split-K units moved behind the grid barrier onto workgroups 224..255; gate-up-side transposes moved to the same point, sized per workgroup class
# speedup vs baseline: 1.0003x; 1.0003x over previous
; #define LAS __attribute__((address_space(3)))
; __device__ __forceinline__ unsigned xb_add(unsigned* p, unsigned v) { return __hip_atomic_fetch_add(p, v, __ATOMIC_RELAXED, __HIP_MEMORY_SCOPE_AGENT); }
; __device__ __forceinline__ unsigned xb_xcc_id() { return (unsigned)__builtin_amdgcn_s_getreg((3 << 11) | 20) & 0xFu; }
; __global__ void __launch_bounds__(512, 2) hybrid_fwd(Params P) {
;     ...
;     const int G0 = gridDim.x, bid0 = blockIdx.x;
;     const int wave0 = __builtin_amdgcn_readfirstlane((int)threadIdx.x >> 6);
;     ...
;     cg::this_grid().sync();
;     ...
;     LAS unsigned long long* ptab = (LAS unsigned long long*)(ldsl + PTAB_OFF);
;     if (threadIdx.x == 0) {
; #pragma unroll
;         for (int i = 0; i < 34; ++i) ptab[i] = (unsigned long long)P.in[i];
;         ptab[34] = (unsigned long long)P.out; ptab[35] = (unsigned long long)P.ws;
;         ((volatile LAS unsigned*)(ldsl + XBST_OFF))[0] = 0u; ((volatile LAS unsigned*)(ldsl + XBST_OFF))[1] = 0u;
;         (void)xb_add((unsigned*)P.ws + XB_XCNT(xb_xcc_id()), 1u); }
_Z10hybrid_fwd6Params:
	v_mov_b32_e32 v255, 0
	v_writelane_b32 v252, 0, 41
	s_add_u32 s4, s0, 0x128
	v_writelane_b32 v253, s2, 0
	s_load_dword s2, s[0:1], 0x128
	v_and_b32_e32 v1, 0x3ff, v0
	v_and_b32_e32 v0, 0x3fffffff, v0
	s_addc_u32 s5, s1, 0
	v_readfirstlane_b32 s26, v1
	s_waitcnt lgkmcnt(0)
	v_writelane_b32 v253, s2, 1
	v_cmp_eq_u32_e32 vcc, 0, v1
	s_and_saveexec_b64 s[2:3], vcc
	s_cbranch_execz .LBB0_13
	s_load_dwordx16 s[8:23], s[0:1], 0x0
	s_add_i32 s4, 0, 0x20400
	v_mov_b32_e32 v4, s4
	s_add_i32 s4, 0, 0x20410
	s_load_dwordx16 s[36:51], s[0:1], 0x80
	s_waitcnt lgkmcnt(0)
	v_mov_b32_e32 v0, s8
	v_mov_b32_e32 v1, s9
	v_mov_b32_e32 v2, s10
	v_mov_b32_e32 v3, s11
	ds_write_b128 v4, v[0:3]
	v_mov_b32_e32 v0, s12
	v_mov_b32_e32 v1, s13
	v_mov_b32_e32 v2, s14
	v_mov_b32_e32 v3, s15
	v_mov_b32_e32 v4, s4
	s_add_i32 s4, 0, 0x20420
	ds_write_b128 v4, v[0:3]
	v_mov_b32_e32 v0, s16
	v_mov_b32_e32 v1, s17
	v_mov_b32_e32 v2, s18
	v_mov_b32_e32 v3, s19
	v_mov_b32_e32 v4, s4
	s_load_dwordx16 s[4:19], s[0:1], 0x40
	ds_write_b128 v4, v[0:3]
	v_mov_b32_e32 v0, s20
	s_add_i32 s20, 0, 0x20430
	v_mov_b32_e32 v1, s21
	v_mov_b32_e32 v2, s22
	v_mov_b32_e32 v3, s23
	v_mov_b32_e32 v4, s20
	ds_write_b128 v4, v[0:3]
	s_waitcnt lgkmcnt(0)
	v_mov_b32_e32 v0, s4
	s_add_i32 s4, 0, 0x20440
	v_mov_b32_e32 v1, s5
	v_mov_b32_e32 v2, s6
	v_mov_b32_e32 v3, s7
	v_mov_b32_e32 v4, s4
	s_add_i32 s4, 0, 0x20450
	ds_write_b128 v4, v[0:3]
	v_mov_b32_e32 v0, s8
	v_mov_b32_e32 v1, s9
	v_mov_b32_e32 v2, s10
	v_mov_b32_e32 v3, s11
	v_mov_b32_e32 v4, s4
	s_add_i32 s4, 0, 0x20460
	ds_write_b128 v4, v[0:3]
	v_mov_b32_e32 v0, s12
	v_mov_b32_e32 v1, s13
	v_mov_b32_e32 v2, s14
	v_mov_b32_e32 v3, s15
	v_mov_b32_e32 v4, s4
	s_add_i32 s4, 0, 0x20470
	ds_write_b128 v4, v[0:3]
	v_mov_b32_e32 v0, s16
	v_mov_b32_e32 v1, s17
	v_mov_b32_e32 v2, s18
	v_mov_b32_e32 v3, s19
	v_mov_b32_e32 v4, s4
	s_add_i32 s4, 0, 0x20480
	ds_write_b128 v4, v[0:3]
	v_mov_b32_e32 v0, s36
	v_mov_b32_e32 v1, s37
	v_mov_b32_e32 v2, s38
	v_mov_b32_e32 v3, s39
	v_mov_b32_e32 v4, s4
	s_add_i32 s4, 0, 0x20490
	ds_write_b128 v4, v[0:3]
	v_mov_b32_e32 v0, s40
	v_mov_b32_e32 v1, s41
	v_mov_b32_e32 v2, s42
	v_mov_b32_e32 v3, s43
	v_mov_b32_e32 v4, s4
	s_add_i32 s4, 0, 0x204a0
	ds_write_b128 v4, v[0:3]
	v_mov_b32_e32 v4, s4
	s_load_dwordx16 s[4:19], s[0:1], 0xc0
	v_mov_b32_e32 v0, s44
	v_mov_b32_e32 v1, s45
	v_mov_b32_e32 v2, s46
	v_mov_b32_e32 v3, s47
	s_add_i32 s20, 0, 0x204b0
	ds_write_b128 v4, v[0:3]
	v_mov_b32_e32 v0, s48
	v_mov_b32_e32 v1, s49
	v_mov_b32_e32 v2, s50
	v_mov_b32_e32 v3, s51
	v_mov_b32_e32 v4, s20
	ds_write_b128 v4, v[0:3]
	s_waitcnt lgkmcnt(0)
	v_mov_b32_e32 v0, s4
	s_add_i32 s4, 0, 0x204c0
	v_mov_b32_e32 v1, s5
	v_mov_b32_e32 v2, s6
	v_mov_b32_e32 v3, s7
	v_mov_b32_e32 v4, s4
	s_add_i32 s4, 0, 0x204d0
	ds_write_b128 v4, v[0:3]
	v_mov_b32_e32 v0, s8
	v_mov_b32_e32 v1, s9
	v_mov_b32_e32 v2, s10
	v_mov_b32_e32 v3, s11
	v_mov_b32_e32 v4, s4
	s_add_i32 s4, 0, 0x204e0
	ds_write_b128 v4, v[0:3]
	v_mov_b32_e32 v4, s4
	s_load_dwordx8 s[4:11], s[0:1], 0x100
	v_mov_b32_e32 v0, s12
	v_mov_b32_e32 v1, s13
	v_mov_b32_e32 v2, s14
	v_mov_b32_e32 v3, s15
	s_add_i32 s12, 0, 0x204f0
	ds_write_b128 v4, v[0:3]
	v_mov_b32_e32 v0, s16
	v_mov_b32_e32 v1, s17
	v_mov_b32_e32 v2, s18
	v_mov_b32_e32 v3, s19
	v_mov_b32_e32 v4, s12
	ds_write_b128 v4, v[0:3]
	s_waitcnt lgkmcnt(0)
	v_mov_b32_e32 v0, s4
	s_add_i32 s4, 0, 0x20500
	v_mov_b32_e32 v1, s5
	v_mov_b32_e32 v2, s6
	v_mov_b32_e32 v3, s7
	v_mov_b32_e32 v4, s4
	s_add_i32 s4, 0, 0x20510
	ds_write_b128 v4, v[0:3]
	v_mov_b32_e32 v0, s8
	v_mov_b32_e32 v1, s9
	v_mov_b32_e32 v2, s10
	v_mov_b32_e32 v3, s11
	v_mov_b32_e32 v4, s4
	s_add_i32 s4, 0, 0x20600
	ds_write_b128 v4, v[0:3]
	v_mov_b32_e32 v0, 0
	v_mov_b32_e32 v1, s4
	s_add_i32 s4, 0, 0x20604
	s_mov_b64 s[24:25], exec
	ds_write_b32 v1, v0
	v_mov_b32_e32 v1, s4
	ds_write_b32 v1, v0
	v_mbcnt_lo_u32_b32 v0, s24, 0
	v_mbcnt_hi_u32_b32 v0, s25, v0
	s_getreg_b32 s4, hwreg(HW_REG_XCC_ID, 0, 4)
	v_cmp_eq_u32_e32 vcc, 0, v0
	s_and_b64 exec, exec, vcc
	s_cbranch_execz .LBB0_13
	s_lshl_b32 s4, s4, 8
	s_and_b32 s4, s4, 0xf00
	s_bcnt1_i32_b64 s5, s[24:25]
	v_mov_b32_e32 v0, s4
	v_mov_b32_e32 v1, s5
	global_atomic_add v0, v1, s[10:11] offset:1024

; #define INP(i) ((const float*)ld_ptr(pb, (i)))
; #define PHASE_END if (ph + 1 < hi) grid_barrier((unsigned*)ws, (unsigned)G, tid, (volatile LAS unsigned*)(ldsl + XBST_OFF)); } ++ph;
; __global__ void __launch_bounds__(512, 2) hybrid_fwd(Params P) {
;     ...
;     for (int l = 0; l < DEPTH; ++l) {
;         PHASE_BEGIN
;         {
;             pg8::Gemm g{XN, WIN + (size_t)l * NIN * D, D, D, D, 0, 0}; pg8::Order S; S.init(M / 256, NIN / 256, 1, G, bid, D / 64);
;             EpiIn E{Qb, Kb, Vb, ZUT, VC, ZUS, ROPE, out, l};
;             pg8::gemm_phase<EpiIn, true>(ldsl, g, S, E, wave);
;         }
;         PHASE_END
;     ...
;             pg8::Gemm g{MIX, WOUT + (size_t)l * D * D, D, D, D, 0, 0}; pg8::Order S; S.init_split(MP / 256, MS / 256, D / 256, G, bid, D / 64);
;             EpiRes E{l == 0 ? INP(0) : nullptr, INP(1), X, (MOD + (size_t)l * NMODROWS * 6144) + 2048, (float*)(ws + WS_PART)};
.LBB0_383:
	s_mov_b64 s[0:1], 64
	v_writelane_b32 v253, s0, 3
	s_mov_b32 s75, 0
	s_movk_i32 s76, 0x2000
	v_writelane_b32 v253, s1, 4
	s_mov_b64 s[0:1], 0
	v_writelane_b32 v253, s0, 5
	v_mov_b32_e32 v161, 0
	s_movk_i32 s77, 0x4000
	v_writelane_b32 v253, s1, 6
	s_add_i32 s0, 0, 0x20400
	v_writelane_b32 v253, s0, 7
	s_add_i32 s0, 0, 0x20600
	v_writelane_b32 v253, s0, 8
	s_add_i32 s0, 0, 0x20604
	v_writelane_b32 v253, s0, 9
	v_writelane_b32 v253, s78, 10
	s_movk_i32 s80, 0x6000
	s_mov_b64 s[82:83], 0x80
	v_mov_b64_e32 v[162:163], 0x18c
	v_mov_b64_e32 v[164:165], 0x18b
	s_movk_i32 s81, 0x1000
	s_movk_i32 s84, 0x3fff
	s_movk_i32 s85, 0x300
	s_movk_i32 s33, 0x80
	s_movk_i32 s86, 0x90
	s_movk_i32 s87, 0xf7f
	s_mov_b32 s88, 0x3e000000
	v_mov_b32_e32 v198, 0x1000
	v_mov_b32_e32 v199, 0x2000
	v_mov_b32_e32 v200, 0x3000
	v_mov_b32_e32 v201, 1
	s_movk_i32 s92, 0x7f
	s_movk_i32 s24, 0x7e
	s_movk_i32 s89, 0x3000
	s_mov_b64 s[90:91], 0x4000
	s_movk_i32 s93, 0x5000
	s_movk_i32 s94, 0x7000
	v_mov_b32_e32 v202, 0x358637bd
	s_mov_b32 s95, 0xf800000
	v_mov_b32_e32 v203, 0x260
	v_mov_b32_e32 v204, 0x800
	v_mov_b32_e32 v205, 0xf149f2ca
	v_mov_b64_e32 v[166:167], 0x42
	v_mov_b64_e32 v[168:169], 0x41
	v_mov_b64_e32 v[170:171], 0x100
	v_mov_b64_e32 v[172:173], 0xff
	v_mov_b64_e32 v[174:175], 0x100
	v_mov_b32_e32 v206, 0x6000
	v_mov_b64_e32 v[176:177], 0x5ac
	v_mov_b64_e32 v[178:179], 0x5ab
	v_mov_b64_e32 v[180:181], 0x158
	v_mov_b64_e32 v[182:183], 0x157
	s_mov_b32 s96, s75
	v_writelane_b32 v253, s79, 11
	s_branch .LBB0_387

; #define INP(i) ((const float*)ld_ptr(pb, (i)))
; __global__ void __launch_bounds__(512, 2) hybrid_fwd(Params P) {
;     ...
;             pg8::Gemm g{MIX, WOUT + (size_t)l * D * D, D, D, D, 0, 0}; pg8::Order S; S.init_split(MP / 256, MS / 256, D / 256, G, bid, D / 64);
;             EpiRes E{l == 0 ? INP(0) : nullptr, INP(1), X, (MOD + (size_t)l * NMODROWS * 6144) + 2048, (float*)(ws + WS_PART)};
;             pg8::gemm_phase<EpiRes, true>(ldsl, g, S, E, wave);
.Lmy_sl_body:
	v_readlane_b32 s0, v253, 7
	v_readlane_b32 s44, v253, 0
	v_readlane_b32 s1, v252, 41
	s_nop 3
	s_lshl_b32 s1, s1, 5
	s_add_i32 s44, s44, s1
	v_readlane_b32 s42, v253, 1
	v_readlane_b32 s43, v253, 2
	v_mov_b32_e32 v0, s0
	v_mbcnt_lo_u32_b32 v154, -1, 0
	v_mbcnt_hi_u32_b32 v154, -1, v154
	ds_read_b64 v[2:3], v0 offset:280
	s_cmp_lg_u32 s96, 0
	s_mov_b64 s[8:9], 0
	s_waitcnt lgkmcnt(0)
	v_readfirstlane_b32 s7, v3
	v_readfirstlane_b32 s6, v2
	s_cbranch_scc1 .LBB0_1411
	ds_read_b64 v[2:3], v0
	s_waitcnt lgkmcnt(0)
	v_readfirstlane_b32 s9, v3
	v_readfirstlane_b32 s8, v2

; #define LAS __attribute__((address_space(3)))
; __device__ __forceinline__ unsigned xb_add(unsigned* p, unsigned v) { return __hip_atomic_fetch_add(p, v, __ATOMIC_RELAXED, __HIP_MEMORY_SCOPE_AGENT); }
; __device__ __forceinline__ unsigned xb_xcc_id() { return (unsigned)__builtin_amdgcn_s_getreg((3 << 11) | 20) & 0xFu; }
; __device__ __forceinline__ void grid_barrier(unsigned* bar, unsigned G, int tid, volatile LAS unsigned* st) {
;     asm volatile("s_waitcnt vmcnt(0) lgkmcnt(0)" ::: "memory");
;     __syncthreads();
;     if (tid == 0) {
;         const unsigned x = xb_xcc_id();
;         unsigned nloc = st[0], nx = st[1];
;         if (nloc == 0u) { xcd_barrier_complete(bar, x, G, nloc, nx); st[0] = nloc; st[1] = nx; }
;         const unsigned old = xb_add(&bar[XB_XSUB(x)], 1u);
.LBB0_1651:
	s_add_i32 s22, s73, 5
	v_readlane_b32 s0, v252, 41
	s_nop 3
	s_cmp_lg_u32 s0, 0
	s_cbranch_scc0 .Lmy_sl_normal
	v_writelane_b32 v252, 0, 41
	s_branch .Lmy_sl_ret
.Lmy_sl_normal:
	s_cmp_ge_i32 s22, s79
	s_cbranch_scc1 .LBB0_1705
	s_waitcnt vmcnt(0) lgkmcnt(0)
	s_lshl_b32 s0, s43, 6
	v_sub_u32_e32 v0, 0, v154
	v_cmp_eq_u32_e32 vcc, s0, v0
	s_waitcnt vmcnt(0)
	s_barrier
	s_and_saveexec_b64 s[0:1], vcc
	s_cbranch_execz .LBB0_1704
	v_readlane_b32 s3, v253, 8
	s_getreg_b32 s2, hwreg(HW_REG_XCC_ID, 0, 4)
	s_and_b32 s18, s2, 15
	v_mov_b32_e32 v0, s3
	ds_read_b32 v2, v0
	v_readlane_b32 s3, v253, 9
	s_waitcnt lgkmcnt(0)
	v_cmp_ne_u32_e32 vcc, 0, v2
	v_mov_b32_e32 v0, s3
	ds_read_b32 v0, v0
	s_cbranch_vccnz .LBB0_1668
	s_add_u32 s2, s6, 0x1000
	s_addc_u32 s3, s7, 0
	s_add_u32 s4, s6, 0x1100
	s_addc_u32 s5, s7, 0
	s_add_u32 s8, s6, 0x1200
	s_addc_u32 s9, s7, 0
	s_add_u32 s10, s6, 0x1300
	s_addc_u32 s11, s7, 0
	s_mov_b32 s19, 1
	s_branch .LBB0_1656

; #define INP(i) ((const float*)ld_ptr(pb, (i)))
; __global__ void __launch_bounds__(512, 2) hybrid_fwd(Params P) {
;     ...
;         for (int it = gw; it < DEPTH * I_LAYER; it += NGW) {
;             const int l = it / I_LAYER; int r = it % I_LAYER;
;             if (r < I_IN) { const int kb = r / 48, nbk = r % 48; transpose_item(INP(13) + (size_t)l * D * NIN, D, NIN, WIN + (size_t)l * NIN * D, nbk * 32, kb * 64, win_dst_row(nbk * 32), scr, lane); continue; } r -= I_IN;
;             if (r < I_OUT) { const int kb = r / 32, nbk = r % 32; transpose_item(INP(29) + (size_t)l * D * D, D, D, WOUT + (size_t)l * D * D, nbk * 32, kb * 64, nbk * 32, scr, lane); continue; } r -= I_OUT;
;             if (r < I_G) { const int kb = r / 88, nbk = r % 88, n0 = nbk * 32; transpose_item(INP(30) + (size_t)l * D * DFF, D, DFF, WGU + (size_t)l * NGU * D, n0, kb * 64, 256 * (n0 >> 7) + (n0 & 127), scr, lane); continue; } r -= I_G;
;             if (r < I_G) { const int kb = r / 88, nbk = r % 88, n0 = nbk * 32; transpose_item(INP(31) + (size_t)l * D * DFF, D, DFF, WGU + (size_t)l * NGU * D, n0, kb * 64, 256 * (n0 >> 7) + 128 + (n0 & 127), scr, lane); continue; } r -= I_G;
;             if (r < I_DN) { const int kb = r / 32, nbk = r % 32; transpose_item(INP(32) + (size_t)l * DFF * D, DFF, D, WDN + (size_t)l * D * DFF, nbk * 32, kb * 64, nbk * 32, scr, lane); continue; } r -= I_DN;
.LBB0_1705:
	v_readlane_b32 s0, v253, 0
	s_nop 3
	s_cmpk_lt_u32 s0, 0xe0
	s_cbranch_scc1 .Lmy_sl_ret
	v_writelane_b32 v252, 1, 41
	s_branch .Lmy_sl_body
.Lmy_sl_ret:
	v_readlane_b32 s29, v253, 0
	v_readlane_b32 s30, v253, 2
	s_nop 3
	s_cmp_lt_u32 s29, 172
	s_cbranch_scc1 .Ltr_b_end
	s_sub_u32 s31, s29, 224
	s_mov_b32 s65, 4984
	s_mov_b32 s67, 5536
	s_mov_b32 s66, 256
	s_cmp_lt_u32 s29, 224
	s_cbranch_scc0 .Ltr_b_cls
	s_sub_u32 s31, s29, 192
	s_mov_b32 s65, 3768
	s_mov_b32 s67, 4984
	s_cmp_lt_u32 s29, 192
	s_cbranch_scc0 .Ltr_b_cls
	s_sub_u32 s31, s29, 172
	s_mov_b32 s65, 2688
	s_mov_b32 s67, 3768
	s_mov_b32 s66, 160
.Ltr_b_cls:
	s_lshl_b32 s29, s31, 3
	s_add_u32 s29, s29, s30
	s_cmp_lt_u32 s96, 3
	s_cbranch_scc0 .Ltr_b_end
	s_add_i32 s37, s96, 1
	v_mbcnt_lo_u32_b32 v6, -1, 0
	v_mbcnt_hi_u32_b32 v6, -1, v6
	v_lshrrev_b32_e32 v7, 5, v6
	v_and_b32_e32 v6, 31, v6
	s_add_u32 s0, s29, s65
	s_mov_b32 s1, s67
	s_cmp_lt_u32 s0, s1
	s_cbranch_scc0 .Ltr_b_end

; __global__ void __launch_bounds__(512, 2) hybrid_fwd(Params P) {
;     ...
;         for (int it = gw; it < DEPTH * I_LAYER; it += NGW) {
.Ltr_b_next:
	s_add_u32 s0, s0, s66
	s_cmp_lt_u32 s0, s1
	s_cbranch_scc1 .Ltr_b_item
